# removed the redundant L1 invalidate (buffer_inv) at the 4 same-CU qx/P hand-offs inside the cross-attention phase
# speedup vs baseline: 1.0194x; 1.0071x over previous
; __global__ void __launch_bounds__(512, 2) mk_fwd(Args a) {
;     ...
;                     asm volatile("s_waitcnt vmcnt(0)" ::: "memory"); __syncthreads(); if (tid == 0) { __builtin_amdgcn_fence(__ATOMIC_ACQUIRE, "agent"); asm volatile("s_waitcnt vmcnt(0)" ::: "memory"); } __syncthreads();
;                     const Gemm gs{qx, kmem, M, D, 256, D, D, 256, 256};
;                     const pg8::EpiSoftmax Es{Pb, D};
;                     gemm_phase<pg8::EpiSoftmax, StaticOrder, false, true>(lds, gs, S, Es, tid);
.LBB0_764:
	s_waitcnt vmcnt(0)
	v_cmp_eq_u32_e64 s[4:5], 0, v187
	s_waitcnt vmcnt(0)
	s_barrier
	s_and_saveexec_b64 s[2:3], s[4:5]
	s_cbranch_execz .LBB0_766
.LBB0_766:
	s_or_b64 exec, exec, s[2:3]
	s_add_u32 s18, s74, 0xaa00000
	v_cndmask_b32_e64 v0, 0, 1, s[6:7]
	s_addc_u32 s19, s75, 0
	v_cmp_ne_u32_e64 s[2:3], 1, v0
	s_andn2_b64 vcc, exec, s[6:7]
	v_readfirstlane_b32 s51, v187
	s_barrier
	s_cbranch_vccnz .LBB0_818
	s_lshr_b32 s6, s73, 29
	s_add_i32 s9, s72, s6
	s_and_b32 s6, s9, -8
	s_sub_i32 s20, s72, s6
	s_cmp_gt_i32 s20, -1
	s_cbranch_scc0 .LBB0_769
	s_lshl_b32 s8, s20, 5
	s_cbranch_execz .LBB0_770
	s_branch .LBB0_771

; __global__ void __launch_bounds__(512, 2) mk_fwd(Args a) {
;     ...
;                     asm volatile("s_waitcnt vmcnt(0)" ::: "memory"); __syncthreads(); if (tid == 0) { __builtin_amdgcn_fence(__ATOMIC_ACQUIRE, "agent"); asm volatile("s_waitcnt vmcnt(0)" ::: "memory"); } __syncthreads();
;                     const Gemm go{Pb, vt, M, D, 256, D, 256, 256, 256L * 256};
;                     const pg8::EpiScaleBf16 Eo{ox, D, 1.f, 0, 0, 1.f, nullptr, true};
;                     gemm_phase<pg8::EpiScaleBf16, StaticOrder, true, true>(lds, go, S, Eo, tid);
.LBB0_818:
	s_waitcnt vmcnt(0)
	s_waitcnt vmcnt(0)
	s_barrier
	s_and_saveexec_b64 s[6:7], s[4:5]
	s_cbranch_execz .LBB0_820
.LBB0_820:
	s_or_b64 exec, exec, s[6:7]
	s_add_u32 s8, s74, 0xca00000
	s_addc_u32 s9, s75, 0
	s_and_b64 vcc, exec, s[2:3]
	v_readfirstlane_b32 s6, v187
	s_barrier
	s_cbranch_vccnz .LBB0_866
	s_lshr_b32 s4, s73, 29
	s_add_i32 s7, s72, s4
	s_and_b32 s4, s7, -8
	s_sub_i32 s69, s72, s4
	s_cmp_gt_i32 s69, -1
	s_cselect_b64 s[16:17], -1, 0
	s_and_b64 vcc, exec, s[16:17]
	s_cbranch_vccz .LBB0_823
	s_lshl_b32 s20, s69, 5
	s_mov_b64 s[4:5], 0
	s_branch .LBB0_824

; __global__ void __launch_bounds__(512, 2) mk_fwd(Args a) {
;     ...
;                     asm volatile("s_waitcnt vmcnt(0)" ::: "memory"); __syncthreads(); if (tid == 0) { __builtin_amdgcn_fence(__ATOMIC_ACQUIRE, "agent"); asm volatile("s_waitcnt vmcnt(0)" ::: "memory"); } __syncthreads();
;                     const Gemm gs{qx, kmem, M, D, 256, D, D, 256, 256};
;                     const pg8::EpiSoftmax Es{Pb, D};
;                     gemm_phase<pg8::EpiSoftmax, StaticOrder, false, true>(lds, gs, S, Es, tid);
.LBB0_1799:
	s_waitcnt vmcnt(0)
	v_cmp_eq_u32_e64 s[4:5], 0, v187
	s_waitcnt vmcnt(0)
	s_barrier
	s_and_saveexec_b64 s[2:3], s[4:5]
	s_cbranch_execz .LBB0_1801
.LBB0_1801:
	s_or_b64 exec, exec, s[2:3]
	s_add_u32 s18, s74, 0xaa00000
	v_cndmask_b32_e64 v0, 0, 1, s[6:7]
	s_addc_u32 s19, s75, 0
	v_cmp_ne_u32_e64 s[2:3], 1, v0
	s_andn2_b64 vcc, exec, s[6:7]
	v_readfirstlane_b32 s51, v187
	s_barrier
	s_cbranch_vccnz .LBB0_1853
	s_lshr_b32 s6, s73, 29
	s_add_i32 s9, s72, s6
	s_and_b32 s6, s9, -8
	s_sub_i32 s20, s72, s6
	s_cmp_gt_i32 s20, -1
	s_cbranch_scc0 .LBB0_1804
	s_lshl_b32 s8, s20, 5
	s_cbranch_execz .LBB0_1805
	s_branch .LBB0_1806

; __global__ void __launch_bounds__(512, 2) mk_fwd(Args a) {
;     ...
;                     asm volatile("s_waitcnt vmcnt(0)" ::: "memory"); __syncthreads(); if (tid == 0) { __builtin_amdgcn_fence(__ATOMIC_ACQUIRE, "agent"); asm volatile("s_waitcnt vmcnt(0)" ::: "memory"); } __syncthreads();
;                     const Gemm go{Pb, vt, M, D, 256, D, 256, 256, 256L * 256};
;                     const pg8::EpiScaleBf16 Eo{ox, D, 1.f, 0, 0, 1.f, nullptr, true};
;                     gemm_phase<pg8::EpiScaleBf16, StaticOrder, true, true>(lds, go, S, Eo, tid);
.LBB0_1853:
	s_waitcnt vmcnt(0)
	s_waitcnt vmcnt(0)
	s_barrier
	s_and_saveexec_b64 s[6:7], s[4:5]
	s_cbranch_execz .LBB0_1855
.LBB0_1855:
	s_or_b64 exec, exec, s[6:7]
	s_add_u32 s8, s74, 0xca00000
	s_addc_u32 s9, s75, 0
	s_and_b64 vcc, exec, s[2:3]
	v_readfirstlane_b32 s6, v187
	s_barrier
	s_cbranch_vccnz .LBB0_1901
	s_lshr_b32 s4, s73, 29
	s_add_i32 s7, s72, s4
	s_and_b32 s4, s7, -8
	s_sub_i32 s69, s72, s4
	s_cmp_gt_i32 s69, -1
	s_cselect_b64 s[16:17], -1, 0
	s_and_b64 vcc, exec, s[16:17]
	s_cbranch_vccz .LBB0_1858
	s_lshl_b32 s20, s69, 5
	s_mov_b64 s[4:5], 0
	s_branch .LBB0_1859
